# MLA unit prologue: counted vmcnt(6) so Q scaling overlaps the initial LDS-DMA latency
# baseline (speedup 1.0000x reference)
; DI unsigned cvtpk(float lo, float hi) { f32x2 v = {lo, hi}; bf16x2_t b = __builtin_convertvector(v, bf16x2_t); return __builtin_bit_cast(unsigned, b); }
; template <int DQK, int DV, int kpitch, int vpitch>
; DI void attn_map(LAS unsigned char* lds, const bf16x8 (&qf)[DQK / 16], const bf16* Kg, const bf16* Vg, f32x16 (&o)[DV / 32], float& lsum, int tid, int lane) {
;     ...
;     float l0 = 0.f, l1 = 0.f, l2 = 0.f, l3 = 0.f;
; #pragma unroll
;     for (int d = 0; d < DV / 32; ++d)
; #pragma unroll
;         for (int i = 0; i < 16; ++i) o[d][i] = 0.f;
; DI void mla_unit(const Params& p, LAS unsigned char* lds, int b, int head, int qb, int tid, int lane, int wave) {
;     ...
;     const float sq = rsqrtf((QSSN[row * 8 + head] + QSSP[row * 8 + head]) * (1.f / 96.f) + EPS) * (LOG2E * 0.10206207261596575f);
;     bf16x8 qf[6];
; #pragma unroll
;     for (int ks = 0; ks < 6; ++ks) { const bf16x8 raw = *(const bf16x8*)(QM + row * 768 + head * 96 + ks * 16 + h * 8); u32x4 w;
;         w.x = cvtpk(bf2f(raw[0]) * sq, bf2f(raw[1]) * sq); w.y = cvtpk(bf2f(raw[2]) * sq, bf2f(raw[3]) * sq); w.z = cvtpk(bf2f(raw[4]) * sq, bf2f(raw[5]) * sq); w.w = cvtpk(bf2f(raw[6]) * sq, bf2f(raw[7]) * sq);
;         qf[ks] = __builtin_bit_cast(bf16x8, w); }
.LBB0_1951:
	s_waitcnt vmcnt(6)
	v_add_f32_e32 v26, v26, v27
	v_fmamk_f32 v26, v26, 0x3c2aaaab, v232
	v_mul_f32_e32 v27, 0x4b800000, v26
	v_cmp_gt_f32_e32 vcc, s74, v26
	v_bfe_u32 v28, v150, 2, 2
	v_lshlrev_b32_e32 v30, 4, v25
	v_cndmask_b32_e32 v26, v26, v27, vcc
	v_rsq_f32_e32 v26, v26
	v_lshl_or_b32 v25, v25, 2, v28
	v_and_b32_e32 v27, 16, v150
	v_lshlrev_b32_e32 v28, 2, v150
	v_and_or_b32 v27, v28, 12, v27
	v_mul_f32_e32 v28, 0x45800000, v26
	v_cndmask_b32_e32 v26, v26, v28, vcc
	v_mul_f32_e32 v26, 0x3e16c740, v26
	v_and_b32_e32 v29, 0xffff0000, v20
	v_lshlrev_b32_e32 v28, 16, v20
	v_pk_mul_f32 v[28:29], v[26:27], v[28:29] op_sel_hi:[0,1]
	v_cvt_pk_bf16_f32 v104, v28, v29
	v_and_b32_e32 v29, 0xffff0000, v21
	v_lshlrev_b32_e32 v28, 16, v21
	v_pk_mul_f32 v[20:21], v[26:27], v[28:29] op_sel_hi:[0,1]
	v_cvt_pk_bf16_f32 v105, v20, v21
	v_and_b32_e32 v21, 0xffff0000, v22
	v_lshlrev_b32_e32 v20, 16, v22
	v_pk_mul_f32 v[20:21], v[26:27], v[20:21] op_sel_hi:[0,1]
	v_cvt_pk_bf16_f32 v106, v20, v21
	v_and_b32_e32 v21, 0xffff0000, v23
	v_lshlrev_b32_e32 v20, 16, v23
	v_pk_mul_f32 v[20:21], v[26:27], v[20:21] op_sel_hi:[0,1]
	v_cvt_pk_bf16_f32 v107, v20, v21
	v_and_b32_e32 v21, 0xffff0000, v16
	v_lshlrev_b32_e32 v20, 16, v16
	v_pk_mul_f32 v[20:21], v[26:27], v[20:21] op_sel_hi:[0,1]
	v_cvt_pk_bf16_f32 v108, v20, v21
	v_and_b32_e32 v21, 0xffff0000, v17
	v_lshlrev_b32_e32 v20, 16, v17
	v_pk_mul_f32 v[16:17], v[26:27], v[20:21] op_sel_hi:[0,1]
	v_cvt_pk_bf16_f32 v109, v16, v17
	v_and_b32_e32 v17, 0xffff0000, v18
	v_lshlrev_b32_e32 v16, 16, v18
	v_pk_mul_f32 v[16:17], v[26:27], v[16:17] op_sel_hi:[0,1]
	v_cvt_pk_bf16_f32 v110, v16, v17
	v_and_b32_e32 v17, 0xffff0000, v19
	v_lshlrev_b32_e32 v16, 16, v19
	v_pk_mul_f32 v[16:17], v[26:27], v[16:17] op_sel_hi:[0,1]
	v_cvt_pk_bf16_f32 v111, v16, v17
	v_and_b32_e32 v17, 0xffff0000, v12
	v_lshlrev_b32_e32 v16, 16, v12
	v_pk_mul_f32 v[16:17], v[26:27], v[16:17] op_sel_hi:[0,1]
	v_cvt_pk_bf16_f32 v112, v16, v17
	v_and_b32_e32 v17, 0xffff0000, v13
	v_lshlrev_b32_e32 v16, 16, v13
	v_pk_mul_f32 v[12:13], v[26:27], v[16:17] op_sel_hi:[0,1]
	v_cvt_pk_bf16_f32 v113, v12, v13
	v_and_b32_e32 v13, 0xffff0000, v14
	v_lshlrev_b32_e32 v12, 16, v14
	v_pk_mul_f32 v[12:13], v[26:27], v[12:13] op_sel_hi:[0,1]
	v_cvt_pk_bf16_f32 v114, v12, v13
	v_and_b32_e32 v13, 0xffff0000, v15
	v_lshlrev_b32_e32 v12, 16, v15
	v_pk_mul_f32 v[12:13], v[26:27], v[12:13] op_sel_hi:[0,1]
	v_cvt_pk_bf16_f32 v115, v12, v13
	v_and_b32_e32 v13, 0xffff0000, v8
	v_lshlrev_b32_e32 v12, 16, v8
	v_pk_mul_f32 v[12:13], v[26:27], v[12:13] op_sel_hi:[0,1]
	v_cvt_pk_bf16_f32 v116, v12, v13
	v_and_b32_e32 v13, 0xffff0000, v9
	v_lshlrev_b32_e32 v12, 16, v9
	v_pk_mul_f32 v[8:9], v[26:27], v[12:13] op_sel_hi:[0,1]
	v_cvt_pk_bf16_f32 v117, v8, v9
	v_and_b32_e32 v9, 0xffff0000, v10
	v_lshlrev_b32_e32 v8, 16, v10
	v_pk_mul_f32 v[8:9], v[26:27], v[8:9] op_sel_hi:[0,1]
	v_cvt_pk_bf16_f32 v118, v8, v9
	v_and_b32_e32 v9, 0xffff0000, v11
	v_lshlrev_b32_e32 v8, 16, v11
	v_pk_mul_f32 v[8:9], v[26:27], v[8:9] op_sel_hi:[0,1]
	v_cvt_pk_bf16_f32 v119, v8, v9
	v_and_b32_e32 v9, 0xffff0000, v4
	v_lshlrev_b32_e32 v8, 16, v4
	v_pk_mul_f32 v[8:9], v[26:27], v[8:9] op_sel_hi:[0,1]
	v_cvt_pk_bf16_f32 v120, v8, v9
	v_and_b32_e32 v9, 0xffff0000, v5
	v_lshlrev_b32_e32 v8, 16, v5
	v_pk_mul_f32 v[4:5], v[26:27], v[8:9] op_sel_hi:[0,1]
	v_cvt_pk_bf16_f32 v121, v4, v5
	v_and_b32_e32 v5, 0xffff0000, v6
	v_lshlrev_b32_e32 v4, 16, v6
	v_pk_mul_f32 v[4:5], v[26:27], v[4:5] op_sel_hi:[0,1]
	v_cvt_pk_bf16_f32 v122, v4, v5
	v_and_b32_e32 v5, 0xffff0000, v7
	v_lshlrev_b32_e32 v4, 16, v7
	v_pk_mul_f32 v[4:5], v[26:27], v[4:5] op_sel_hi:[0,1]
	v_cvt_pk_bf16_f32 v123, v4, v5
	v_and_b32_e32 v5, 0xffff0000, v0
	v_lshlrev_b32_e32 v4, 16, v0
	v_pk_mul_f32 v[4:5], v[26:27], v[4:5] op_sel_hi:[0,1]
	v_cvt_pk_bf16_f32 v124, v4, v5
	v_and_b32_e32 v5, 0xffff0000, v1
	v_lshlrev_b32_e32 v4, 16, v1
	v_pk_mul_f32 v[0:1], v[26:27], v[4:5] op_sel_hi:[0,1]
	v_cvt_pk_bf16_f32 v125, v0, v1
	v_and_b32_e32 v1, 0xffff0000, v2
	v_lshlrev_b32_e32 v0, 16, v2
	v_pk_mul_f32 v[0:1], v[26:27], v[0:1] op_sel_hi:[0,1]
	s_movk_i32 s10, 0xc0
	v_cvt_pk_bf16_f32 v126, v0, v1
	v_and_b32_e32 v1, 0xffff0000, v3
	v_lshlrev_b32_e32 v0, 16, v3
	v_mul_lo_u32 v25, v25, s10
	v_pk_mul_f32 v[0:1], v[26:27], v[0:1] op_sel_hi:[0,1]
	s_movk_i32 s10, 0xd0
	v_mov_b32_e32 v147, 0
	s_lshl_b32 s13, s13, 6
	v_cvt_pk_bf16_f32 v127, v0, v1
	v_mad_u32_u24 v151, v24, s10, v30
	s_lshl_b32 s23, s23, 10
	s_lshl_b32 s24, s24, 10
	s_lshl_b32 s25, s25, 10
	v_lshl_or_b32 v152, v27, 1, v25
	s_mov_b32 s27, 0
	v_mov_b32_e32 v149, 0
	v_mov_b32_e32 v146, 0
	v_mov_b32_e32 v148, 0
	v_mov_b32_e32 v16, 0
	v_mov_b32_e32 v17, v147
	v_mov_b32_e32 v18, v147
	v_mov_b32_e32 v19, v147
	v_mov_b32_e32 v20, v147
	v_mov_b32_e32 v21, v147
	v_mov_b32_e32 v22, v147
	v_mov_b32_e32 v23, v147
	v_mov_b32_e32 v24, v147
	v_mov_b32_e32 v25, v147
	v_mov_b32_e32 v26, v147
	v_mov_b32_e32 v27, v147
	v_mov_b32_e32 v28, v147
	v_mov_b32_e32 v29, v147
	v_mov_b32_e32 v30, v147
	v_mov_b32_e32 v31, v147
	v_mov_b32_e32 v0, 0
	v_mov_b32_e32 v1, v147
	v_mov_b32_e32 v2, v147
	v_mov_b32_e32 v3, v147
	v_mov_b32_e32 v4, v147
	v_mov_b32_e32 v5, v147
	v_mov_b32_e32 v6, v147
	v_mov_b32_e32 v7, v147
	v_mov_b32_e32 v8, v147
	v_mov_b32_e32 v9, v147
	v_mov_b32_e32 v10, v147
	v_mov_b32_e32 v11, v147
	v_mov_b32_e32 v12, v147
	v_mov_b32_e32 v13, v147
	v_mov_b32_e32 v14, v147
	v_mov_b32_e32 v15, v147
	s_branch .LBB0_1953
